# chain workgroups pull mLSTM output groups right after their chain (before attention units); rest as previous version
# baseline (speedup 1.0000x reference)
.Lchain_pub_done:
	s_or_b64 exec, exec, s[98:99]
	s_and_b64 vcc, exec, s[4:5]
	s_cbranch_vccnz .LBB0_1077
	s_or_b32 s99, s54, 0x80000000
	s_branch .Lp7_pull

.Lp7_ready:
	s_or_b64 exec, exec, s[100:101]
	s_barrier
	s_mov_b64 s[58:59], s[0:1]
	v_mov_b32_e32 v172, v0
	v_mbcnt_lo_u32_b32 v1, -1, 0
	v_mbcnt_hi_u32_b32 v1, -1, v1
	v_and_b32_e32 v236, 64, v1
	s_branch .Lp7_body
.Lp7_done:
	s_bitcmp1_b32 s99, 31
	s_cbranch_scc1 .Lp7_to_attn
	s_mov_b32 s54, s99
	s_mov_b64 s[8:9], -1
	s_branch .LBB0_1671
.Lp7_to_attn:
	s_and_b32 s54, s99, 0x7fffffff
	v_mov_b32_e32 v132, v0
	s_mov_b64 s[26:27], s[0:1]
	v_mbcnt_lo_u32_b32 v1, -1, 0
	s_nop 0
	v_readfirstlane_b32 s40, v132
	s_branch .LBB0_1077
